# baseline (speedup 1.0000x reference)
; __device__ __forceinline__ long mk64(unsigned lo, unsigned hi) { return (long)(((u64)hi << 32) | (u64)lo); }
; #define MFMA8(a, b, c) __builtin_amdgcn_mfma_f32_16x16x32_fp8_fp8(a, b, c, 0, 0, 0)
; __device__ __forceinline__ void phase_peerout(const Params& p, char* smem, float* dstbase) {
;     ...
;       const unsigned char* rp0 = u8 + (size_t)eix[(2 * w) * 16 + fr] * D + fq * 16;
;       const unsigned char* rp1 = u8 + (size_t)eix[(2 * w + 1) * 16 + fr] * D + fq * 16;
;       f32x4 ah0 = {0.f, 0.f, 0.f, 0.f}, ah1 = ah0;
;       const unsigned char* xsel = (fr < 8) ? xhi : xlo;
;       u32x4 ring[8][4];
; #pragma unroll
;       for (int sgi = 0; sgi < 8; ++sgi) {
;         ring[sgi][0] = *(const u32x4*)(rp0 + sgi * 128);
;         ring[sgi][1] = *(const u32x4*)(rp0 + sgi * 128 + 64);
;         ring[sgi][2] = *(const u32x4*)(rp1 + sgi * 128);
;         ring[sgi][3] = *(const u32x4*)(rp1 + sgi * 128 + 64);
;       }
; #pragma unroll
;       for (int kq = 0; kq < 16; ++kq) {
;         const u32x4 c0 = ring[kq & 7][0], c1 = ring[kq & 7][1], c2 = ring[kq & 7][2], c3 = ring[kq & 7][3];
;         if (kq + 8 < 16) {
;           ring[kq & 7][0] = *(const u32x4*)(rp0 + (kq + 8) * 128);
;           ring[kq & 7][1] = *(const u32x4*)(rp0 + (kq + 8) * 128 + 64);
;           ring[kq & 7][2] = *(const u32x4*)(rp1 + (kq + 8) * 128);
;           ring[kq & 7][3] = *(const u32x4*)(rp1 + (kq + 8) * 128 + 64);
;         } else {
; #pragma unroll
;           for (int j = 0; j < 4; ++j) {
;             const int i = (kq - 8) * 4 + j;
;             vpre[i] = *(const u32x4*)(v8 + (size_t)eix[2 * i + (tid >> 7)] * D + (tid & 127) * 16);
;           }
;         }
;         const u32x4 x0 = *(const u32x4*)(xsel + kq * 128 + fq * 16), x1v = *(const u32x4*)(xsel + kq * 128 + fq * 16 + 64);
;         long b;
;         b = mk64(x0[0], x0[1]);
;         ah0 = MFMA8(mk64(c0[0], c0[1]), b, ah0); ah1 = MFMA8(mk64(c2[0], c2[1]), b, ah1);
;         b = mk64(x0[2], x0[3]);
;         ah0 = MFMA8(mk64(c0[2], c0[3]), b, ah0); ah1 = MFMA8(mk64(c2[2], c2[3]), b, ah1);
;         b = mk64(x1v[0], x1v[1]);
;         ah0 = MFMA8(mk64(c1[0], c1[1]), b, ah0); ah1 = MFMA8(mk64(c3[0], c3[1]), b, ah1);
;         b = mk64(x1v[2], x1v[3]);
;         ah0 = MFMA8(mk64(c1[2], c1[3]), b, ah0); ah1 = MFMA8(mk64(c3[2], c3[3]), b, ah1);
;       }
.LBB0_1253:
	ds_read2_b32 v[22:23], v189 offset0:128 offset1:144
	s_waitcnt lgkmcnt(0)
	v_ashrrev_i32_e32 v17, 31, v22
	v_mov_b32_e32 v16, v22
	v_lshlrev_b64 v[16:17], 11, v[16:17]
	v_lshl_add_u64 v[16:17], v[166:167], 0, v[16:17]
	global_load_dwordx4 v[18:21], v[16:17], off
	v_ashrrev_i32_e32 v25, 31, v23
	v_mov_b32_e32 v24, v23
	v_lshlrev_b64 v[22:23], 11, v[24:25]
	v_lshl_add_u64 v[88:89], v[166:167], 0, v[22:23]
	global_load_dwordx4 v[22:25], v[88:89], off
	global_load_dwordx4 v[26:29], v[16:17], off offset:64
	ds_read_b128 v[30:33], v164
	ds_read_b128 v[34:37], v164 offset:64
	global_load_dwordx4 v[42:45], v[88:89], off offset:64
	s_waitcnt vmcnt(2) lgkmcnt(1)
	s_setprio 2
	v_mfma_f32_16x16x32_fp8_fp8 v[46:49], v[22:23], v[30:31], 0
	v_mfma_f32_16x16x32_fp8_fp8 v[38:41], v[18:19], v[30:31], 0
	v_mfma_f32_16x16x32_fp8_fp8 v[18:21], v[20:21], v[32:33], v[38:41]
	v_mfma_f32_16x16x32_fp8_fp8 v[22:25], v[24:25], v[32:33], v[46:49]
	global_load_dwordx4 v[30:33], v[16:17], off offset:128
	s_nop 4
	global_load_dwordx4 v[38:41], v[88:89], off offset:128
	s_waitcnt vmcnt(3) lgkmcnt(0)
	v_mfma_f32_16x16x32_fp8_fp8 v[18:21], v[26:27], v[34:35], v[18:21]
	s_waitcnt vmcnt(2)
	v_mfma_f32_16x16x32_fp8_fp8 v[22:25], v[42:43], v[34:35], v[22:25]
	v_mfma_f32_16x16x32_fp8_fp8 v[18:21], v[28:29], v[36:37], v[18:21]
	global_load_dwordx4 v[26:29], v[16:17], off offset:192
	v_mfma_f32_16x16x32_fp8_fp8 v[22:25], v[44:45], v[36:37], v[22:25]
	ds_read_b128 v[34:37], v164 offset:128
	ds_read_b128 v[42:45], v164 offset:192
	global_load_dwordx4 v[46:49], v[88:89], off offset:192
	s_waitcnt vmcnt(3) lgkmcnt(1)
	v_mfma_f32_16x16x32_fp8_fp8 v[18:21], v[30:31], v[34:35], v[18:21]
	v_mfma_f32_16x16x32_fp8_fp8 v[18:21], v[32:33], v[36:37], v[18:21]
	global_load_dwordx4 v[30:33], v[16:17], off offset:256
	s_waitcnt vmcnt(3)
	v_mfma_f32_16x16x32_fp8_fp8 v[22:25], v[38:39], v[34:35], v[22:25]
	v_mfma_f32_16x16x32_fp8_fp8 v[22:25], v[40:41], v[36:37], v[22:25]
	global_load_dwordx4 v[34:37], v[88:89], off offset:256
	s_waitcnt vmcnt(3) lgkmcnt(0)
	v_mfma_f32_16x16x32_fp8_fp8 v[18:21], v[26:27], v[42:43], v[18:21]
	s_waitcnt vmcnt(2)
	v_mfma_f32_16x16x32_fp8_fp8 v[22:25], v[46:47], v[42:43], v[22:25]
	v_mfma_f32_16x16x32_fp8_fp8 v[18:21], v[28:29], v[44:45], v[18:21]
	global_load_dwordx4 v[26:29], v[16:17], off offset:320
	v_mfma_f32_16x16x32_fp8_fp8 v[22:25], v[48:49], v[44:45], v[22:25]
	ds_read_b128 v[38:41], v164 offset:256
	ds_read_b128 v[42:45], v164 offset:320
	global_load_dwordx4 v[46:49], v[88:89], off offset:320
	s_waitcnt vmcnt(3) lgkmcnt(1)
	v_mfma_f32_16x16x32_fp8_fp8 v[18:21], v[30:31], v[38:39], v[18:21]
	v_mfma_f32_16x16x32_fp8_fp8 v[18:21], v[32:33], v[40:41], v[18:21]
	global_load_dwordx4 v[30:33], v[16:17], off offset:384
	s_waitcnt vmcnt(3)
	v_mfma_f32_16x16x32_fp8_fp8 v[22:25], v[34:35], v[38:39], v[22:25]
	v_mfma_f32_16x16x32_fp8_fp8 v[22:25], v[36:37], v[40:41], v[22:25]
	global_load_dwordx4 v[34:37], v[88:89], off offset:384
	s_waitcnt vmcnt(3) lgkmcnt(0)
	v_mfma_f32_16x16x32_fp8_fp8 v[18:21], v[26:27], v[42:43], v[18:21]
	s_waitcnt vmcnt(2)
	v_mfma_f32_16x16x32_fp8_fp8 v[22:25], v[46:47], v[42:43], v[22:25]
	v_mfma_f32_16x16x32_fp8_fp8 v[18:21], v[28:29], v[44:45], v[18:21]
	global_load_dwordx4 v[26:29], v[16:17], off offset:448
	v_mfma_f32_16x16x32_fp8_fp8 v[22:25], v[48:49], v[44:45], v[22:25]
	ds_read_b128 v[38:41], v164 offset:384
	ds_read_b128 v[42:45], v164 offset:448
	global_load_dwordx4 v[46:49], v[88:89], off offset:448
	s_waitcnt vmcnt(3) lgkmcnt(1)
	v_mfma_f32_16x16x32_fp8_fp8 v[18:21], v[30:31], v[38:39], v[18:21]
	v_mfma_f32_16x16x32_fp8_fp8 v[18:21], v[32:33], v[40:41], v[18:21]
	global_load_dwordx4 v[30:33], v[16:17], off offset:512
	s_waitcnt vmcnt(3)
	v_mfma_f32_16x16x32_fp8_fp8 v[22:25], v[34:35], v[38:39], v[22:25]
	v_mfma_f32_16x16x32_fp8_fp8 v[22:25], v[36:37], v[40:41], v[22:25]
	global_load_dwordx4 v[34:37], v[88:89], off offset:512
	s_waitcnt vmcnt(3) lgkmcnt(0)
	v_mfma_f32_16x16x32_fp8_fp8 v[18:21], v[26:27], v[42:43], v[18:21]
	s_waitcnt vmcnt(2)
	v_mfma_f32_16x16x32_fp8_fp8 v[22:25], v[46:47], v[42:43], v[22:25]
	v_mfma_f32_16x16x32_fp8_fp8 v[18:21], v[28:29], v[44:45], v[18:21]
	global_load_dwordx4 v[26:29], v[16:17], off offset:576
	v_mfma_f32_16x16x32_fp8_fp8 v[22:25], v[48:49], v[44:45], v[22:25]
	ds_read_b128 v[38:41], v164 offset:512
	ds_read_b128 v[42:45], v164 offset:576
	global_load_dwordx4 v[46:49], v[88:89], off offset:576
	s_waitcnt vmcnt(3) lgkmcnt(1)
	v_mfma_f32_16x16x32_fp8_fp8 v[18:21], v[30:31], v[38:39], v[18:21]
	v_mfma_f32_16x16x32_fp8_fp8 v[18:21], v[32:33], v[40:41], v[18:21]
	global_load_dwordx4 v[30:33], v[16:17], off offset:640
	s_waitcnt vmcnt(3)
	v_mfma_f32_16x16x32_fp8_fp8 v[22:25], v[34:35], v[38:39], v[22:25]
	v_mfma_f32_16x16x32_fp8_fp8 v[22:25], v[36:37], v[40:41], v[22:25]
	global_load_dwordx4 v[34:37], v[88:89], off offset:640
	s_waitcnt vmcnt(3) lgkmcnt(0)
	v_mfma_f32_16x16x32_fp8_fp8 v[18:21], v[26:27], v[42:43], v[18:21]
	s_waitcnt vmcnt(2)
	v_mfma_f32_16x16x32_fp8_fp8 v[22:25], v[46:47], v[42:43], v[22:25]
	v_mfma_f32_16x16x32_fp8_fp8 v[18:21], v[28:29], v[44:45], v[18:21]
	global_load_dwordx4 v[26:29], v[16:17], off offset:704
	v_mfma_f32_16x16x32_fp8_fp8 v[22:25], v[48:49], v[44:45], v[22:25]
	ds_read_b128 v[38:41], v164 offset:640
	ds_read_b128 v[42:45], v164 offset:704
	global_load_dwordx4 v[46:49], v[88:89], off offset:704
	global_load_dwordx4 v[50:53], v[88:89], off offset:832
	s_waitcnt vmcnt(4) lgkmcnt(1)
	v_mfma_f32_16x16x32_fp8_fp8 v[18:21], v[30:31], v[38:39], v[18:21]
	v_mfma_f32_16x16x32_fp8_fp8 v[18:21], v[32:33], v[40:41], v[18:21]
	global_load_dwordx4 v[30:33], v[16:17], off offset:768
	s_waitcnt vmcnt(4)
; __device__ __forceinline__ long mk64(unsigned lo, unsigned hi) { return (long)(((u64)hi << 32) | (u64)lo); }
; #define MFMA8(a, b, c) __builtin_amdgcn_mfma_f32_16x16x32_fp8_fp8(a, b, c, 0, 0, 0)
; __device__ __forceinline__ void phase_peerout(const Params& p, char* smem, float* dstbase) {
;     ...
;       for (int kq = 0; kq < 16; ++kq) {
;         const u32x4 c0 = ring[kq & 7][0], c1 = ring[kq & 7][1], c2 = ring[kq & 7][2], c3 = ring[kq & 7][3];
;         if (kq + 8 < 16) {
;           ring[kq & 7][0] = *(const u32x4*)(rp0 + (kq + 8) * 128);
;           ring[kq & 7][1] = *(const u32x4*)(rp0 + (kq + 8) * 128 + 64);
;           ring[kq & 7][2] = *(const u32x4*)(rp1 + (kq + 8) * 128);
;           ring[kq & 7][3] = *(const u32x4*)(rp1 + (kq + 8) * 128 + 64);
;         } else {
; #pragma unroll
;           for (int j = 0; j < 4; ++j) {
;             const int i = (kq - 8) * 4 + j;
;             vpre[i] = *(const u32x4*)(v8 + (size_t)eix[2 * i + (tid >> 7)] * D + (tid & 127) * 16);
;           }
;         }
;         const u32x4 x0 = *(const u32x4*)(xsel + kq * 128 + fq * 16), x1v = *(const u32x4*)(xsel + kq * 128 + fq * 16 + 64);
;         long b;
;         b = mk64(x0[0], x0[1]);
;         ah0 = MFMA8(mk64(c0[0], c0[1]), b, ah0); ah1 = MFMA8(mk64(c2[0], c2[1]), b, ah1);
;         b = mk64(x0[2], x0[3]);
;         ah0 = MFMA8(mk64(c0[2], c0[3]), b, ah0); ah1 = MFMA8(mk64(c2[2], c2[3]), b, ah1);
;         b = mk64(x1v[0], x1v[1]);
;         ah0 = MFMA8(mk64(c1[0], c1[1]), b, ah0); ah1 = MFMA8(mk64(c3[0], c3[1]), b, ah1);
;         b = mk64(x1v[2], x1v[3]);
;         ah0 = MFMA8(mk64(c1[2], c1[3]), b, ah0); ah1 = MFMA8(mk64(c3[2], c3[3]), b, ah1);
	v_mfma_f32_16x16x32_fp8_fp8 v[22:25], v[34:35], v[38:39], v[22:25]
	v_mfma_f32_16x16x32_fp8_fp8 v[22:25], v[36:37], v[40:41], v[22:25]
	global_load_dwordx4 v[34:37], v[88:89], off offset:768
	global_load_dwordx4 v[38:41], v[16:17], off offset:832
	s_waitcnt vmcnt(5) lgkmcnt(0)
	v_mfma_f32_16x16x32_fp8_fp8 v[18:21], v[26:27], v[42:43], v[18:21]
	s_waitcnt vmcnt(4)
	v_mfma_f32_16x16x32_fp8_fp8 v[22:25], v[46:47], v[42:43], v[22:25]
	v_mfma_f32_16x16x32_fp8_fp8 v[18:21], v[28:29], v[44:45], v[18:21]
	global_load_dwordx4 v[26:29], v[16:17], off offset:896
	v_mfma_f32_16x16x32_fp8_fp8 v[22:25], v[48:49], v[44:45], v[22:25]
	ds_read_b128 v[42:45], v164 offset:768
	ds_read_b128 v[46:49], v164 offset:832
	global_load_dwordx4 v[54:57], v[88:89], off offset:896
	global_load_dwordx4 v[96:99], v[16:17], off offset:960
	global_load_dwordx4 v[108:111], v[16:17], off offset:1024
	global_load_dwordx4 v[112:115], v[88:89], off offset:1024
	global_load_dwordx4 v[120:123], v[16:17], off offset:1088
	global_load_dwordx4 v[128:131], v[88:89], off offset:1088
	global_load_dwordx4 v[136:139], v[16:17], off offset:1152
	global_load_dwordx4 v[140:143], v[88:89], off offset:1152
	s_waitcnt vmcnt(11) lgkmcnt(1)
	v_mfma_f32_16x16x32_fp8_fp8 v[18:21], v[30:31], v[42:43], v[18:21]
	v_mfma_f32_16x16x32_fp8_fp8 v[18:21], v[32:33], v[44:45], v[18:21]
	global_load_dwordx4 v[30:33], v[88:89], off offset:960
	s_waitcnt vmcnt(11)
	v_mfma_f32_16x16x32_fp8_fp8 v[22:25], v[34:35], v[42:43], v[22:25]
	v_mfma_f32_16x16x32_fp8_fp8 v[22:25], v[36:37], v[44:45], v[22:25]
	ds_read_b128 v[34:37], v164 offset:896
	ds_read_b128 v[42:45], v164 offset:960
	global_load_dwordx4 v[144:147], v[16:17], off offset:1216
	global_load_dwordx4 v[148:151], v[88:89], off offset:1216
	global_load_dwordx4 v[132:135], v[16:17], off offset:1280
	global_load_dwordx4 v[116:119], v[16:17], off offset:1344
	global_load_dwordx4 v[124:127], v[88:89], off offset:1280
	global_load_dwordx4 v[104:107], v[88:89], off offset:1344
	global_load_dwordx4 v[92:95], v[16:17], off offset:1408
	global_load_dwordx4 v[80:83], v[16:17], off offset:1472
	global_load_dwordx4 v[84:87], v[88:89], off offset:1408
	global_load_dwordx4 v[76:79], v[88:89], off offset:1472
	s_waitcnt vmcnt(20) lgkmcnt(2)
	v_mfma_f32_16x16x32_fp8_fp8 v[18:21], v[38:39], v[46:47], v[18:21]
	global_load_dwordx4 v[72:75], v[16:17], off offset:1536
	global_load_dwordx4 v[64:67], v[16:17], off offset:1600
	global_load_dwordx4 v[68:71], v[88:89], off offset:1536
	global_load_dwordx4 v[60:63], v[88:89], off offset:1600
	v_mfma_f32_16x16x32_fp8_fp8 v[22:25], v[50:51], v[46:47], v[22:25]
	v_mfma_f32_16x16x32_fp8_fp8 v[18:21], v[40:41], v[48:49], v[18:21]
	v_mfma_f32_16x16x32_fp8_fp8 v[22:25], v[52:53], v[48:49], v[22:25]
	s_waitcnt vmcnt(23) lgkmcnt(1)
	v_mfma_f32_16x16x32_fp8_fp8 v[18:21], v[26:27], v[34:35], v[18:21]
	s_waitcnt vmcnt(22)
	v_mfma_f32_16x16x32_fp8_fp8 v[22:25], v[54:55], v[34:35], v[22:25]
	v_mfma_f32_16x16x32_fp8_fp8 v[18:21], v[28:29], v[36:37], v[18:21]
	v_mfma_f32_16x16x32_fp8_fp8 v[22:25], v[56:57], v[36:37], v[22:25]
	s_waitcnt vmcnt(21) lgkmcnt(0)
	v_mfma_f32_16x16x32_fp8_fp8 v[18:21], v[96:97], v[42:43], v[18:21]
	v_mfma_f32_16x16x32_fp8_fp8 v[18:21], v[98:99], v[44:45], v[18:21]
	s_waitcnt vmcnt(14)
	v_mfma_f32_16x16x32_fp8_fp8 v[22:25], v[30:31], v[42:43], v[22:25]
	global_load_dwordx4 v[56:59], v[16:17], off offset:1664
	global_load_dwordx4 v[48:51], v[16:17], off offset:1728
	global_load_dwordx4 v[52:55], v[88:89], off offset:1664
	global_load_dwordx4 v[40:43], v[88:89], off offset:1728
	global_load_dwordx4 v[36:39], v[16:17], off offset:1792
	global_load_dwordx4 v[28:31], v[16:17], off offset:1856
	ds_read_b128 v[96:99], v164 offset:1024
	v_mfma_f32_16x16x32_fp8_fp8 v[194:197], v[32:33], v[44:45], v[22:25]
	global_load_dwordx4 v[44:47], v[88:89], off offset:1792
	global_load_dwordx4 v[32:35], v[88:89], off offset:1856
	ds_read_b128 v[198:201], v164 offset:1088
	s_waitcnt lgkmcnt(1)
	v_mfma_f32_16x16x32_fp8_fp8 v[202:205], v[108:109], v[96:97], v[18:21]
	global_load_dwordx4 v[24:27], v[16:17], off offset:1920
	s_nop 1
	global_load_dwordx4 v[16:19], v[16:17], off offset:1984
	s_nop 0
	global_load_dwordx4 v[20:23], v[88:89], off offset:1920
	global_load_dwordx4 v[100:103], v[88:89], off offset:1984
	v_mfma_f32_16x16x32_fp8_fp8 v[88:91], v[112:113], v[96:97], v[194:197]
	ds_read2_b32 v[96:97], v190 offset0:128 offset1:130
	ds_read2_b32 v[206:207], v190 offset0:132 offset1:134
	ds_read2_b32 v[208:209], v190 offset0:136 offset1:138
	s_waitcnt lgkmcnt(2)
	v_ashrrev_i32_e32 v113, 31, v96
	v_mfma_f32_16x16x32_fp8_fp8 v[108:111], v[110:111], v[98:99], v[202:205]
	v_mov_b32_e32 v112, v96
	v_mfma_f32_16x16x32_fp8_fp8 v[88:91], v[114:115], v[98:99], v[88:91]
	v_lshlrev_b64 v[98:99], 11, v[112:113]
	v_ashrrev_i32_e32 v113, 31, v97
	v_mov_b32_e32 v112, v97
	v_mfma_f32_16x16x32_fp8_fp8 v[108:111], v[120:121], v[198:199], v[108:111]
	v_lshlrev_b64 v[96:97], 11, v[112:113]
	v_lshl_add_u64 v[98:99], v[168:169], 0, v[98:99]
	v_lshl_add_u64 v[96:97], v[168:169], 0, v[96:97]
	v_mfma_f32_16x16x32_fp8_fp8 v[112:115], v[128:129], v[198:199], v[88:91]
	s_waitcnt lgkmcnt(1)
	v_ashrrev_i32_e32 v121, 31, v206
	v_mov_b32_e32 v120, v206
	ds_read2_b32 v[202:203], v190 offset0:140 offset1:142
	global_load_dwordx4 v[88:91], v[98:99], off
	s_nop 0
	global_load_dwordx4 v[96:99], v[96:97], off
	v_mfma_f32_16x16x32_fp8_fp8 v[108:111], v[122:123], v[200:201], v[108:111]
	v_lshlrev_b64 v[128:129], 11, v[120:121]
	ds_read_b128 v[120:123], v164 offset:1152
	ds_read_b128 v[194:197], v164 offset:1216
	v_mfma_f32_16x16x32_fp8_fp8 v[112:115], v[130:131], v[200:201], v[112:115]
	v_ashrrev_i32_e32 v131, 31, v207
	v_mov_b32_e32 v130, v207
	v_lshlrev_b64 v[130:131], 11, v[130:131]
	s_waitcnt lgkmcnt(1)
; __device__ __forceinline__ long mk64(unsigned lo, unsigned hi) { return (long)(((u64)hi << 32) | (u64)lo); }
; #define MFMA8(a, b, c) __builtin_amdgcn_mfma_f32_16x16x32_fp8_fp8(a, b, c, 0, 0, 0)
; __device__ __forceinline__ void phase_peerout(const Params& p, char* smem, float* dstbase) {
;     ...
;       for (int kq = 0; kq < 16; ++kq) {
;         const u32x4 c0 = ring[kq & 7][0], c1 = ring[kq & 7][1], c2 = ring[kq & 7][2], c3 = ring[kq & 7][3];
;         if (kq + 8 < 16) {
;           ring[kq & 7][0] = *(const u32x4*)(rp0 + (kq + 8) * 128);
;           ring[kq & 7][1] = *(const u32x4*)(rp0 + (kq + 8) * 128 + 64);
;           ring[kq & 7][2] = *(const u32x4*)(rp1 + (kq + 8) * 128);
;           ring[kq & 7][3] = *(const u32x4*)(rp1 + (kq + 8) * 128 + 64);
;         } else {
; #pragma unroll
;           for (int j = 0; j < 4; ++j) {
;             const int i = (kq - 8) * 4 + j;
;             vpre[i] = *(const u32x4*)(v8 + (size_t)eix[2 * i + (tid >> 7)] * D + (tid & 127) * 16);
;           }
;         }
;         const u32x4 x0 = *(const u32x4*)(xsel + kq * 128 + fq * 16), x1v = *(const u32x4*)(xsel + kq * 128 + fq * 16 + 64);
;         long b;
;         b = mk64(x0[0], x0[1]);
;         ah0 = MFMA8(mk64(c0[0], c0[1]), b, ah0); ah1 = MFMA8(mk64(c2[0], c2[1]), b, ah1);
;         b = mk64(x0[2], x0[3]);
;         ah0 = MFMA8(mk64(c0[2], c0[3]), b, ah0); ah1 = MFMA8(mk64(c2[2], c2[3]), b, ah1);
;         b = mk64(x1v[0], x1v[1]);
;         ah0 = MFMA8(mk64(c1[0], c1[1]), b, ah0); ah1 = MFMA8(mk64(c3[0], c3[1]), b, ah1);
;         b = mk64(x1v[2], x1v[3]);
;         ah0 = MFMA8(mk64(c1[2], c1[3]), b, ah0); ah1 = MFMA8(mk64(c3[2], c3[3]), b, ah1);
	v_mfma_f32_16x16x32_fp8_fp8 v[108:111], v[136:137], v[120:121], v[108:111]
	v_lshl_add_u64 v[128:129], v[168:169], 0, v[128:129]
	v_lshl_add_u64 v[130:131], v[168:169], 0, v[130:131]
	v_mfma_f32_16x16x32_fp8_fp8 v[198:201], v[140:141], v[120:121], v[112:115]
	v_ashrrev_i32_e32 v141, 31, v209
	v_mov_b32_e32 v140, v209
	v_ashrrev_i32_e32 v121, 31, v208
	v_mfma_f32_16x16x32_fp8_fp8 v[108:111], v[138:139], v[122:123], v[108:111]
	v_mov_b32_e32 v120, v208
	v_lshlrev_b64 v[120:121], 11, v[120:121]
	v_lshl_add_u64 v[120:121], v[168:169], 0, v[120:121]
	v_mfma_f32_16x16x32_fp8_fp8 v[136:139], v[142:143], v[122:123], v[198:201]
	v_lshlrev_b64 v[122:123], 11, v[140:141]
	v_lshl_add_u64 v[122:123], v[168:169], 0, v[122:123]
	global_load_dwordx4 v[112:115], v[128:129], off
	s_nop 0
	global_load_dwordx4 v[128:131], v[130:131], off
	s_waitcnt vmcnt(29) lgkmcnt(0)
	v_mfma_f32_16x16x32_fp8_fp8 v[140:143], v[144:145], v[194:195], v[108:111]
	s_nop 2
	global_load_dwordx4 v[108:111], v[120:121], off
	s_nop 0
	global_load_dwordx4 v[120:123], v[122:123], off
	ds_read_b128 v[198:201], v164 offset:1280
	v_ashrrev_i32_e32 v145, 31, v202
	s_waitcnt vmcnt(30)
	v_mfma_f32_16x16x32_fp8_fp8 v[136:139], v[148:149], v[194:195], v[136:139]
	v_mov_b32_e32 v144, v202
	v_lshlrev_b64 v[144:145], 11, v[144:145]
	v_lshl_add_u64 v[144:145], v[168:169], 0, v[144:145]
	v_mfma_f32_16x16x32_fp8_fp8 v[140:143], v[146:147], v[196:197], v[140:143]
	v_ashrrev_i32_e32 v147, 31, v203
	v_mov_b32_e32 v146, v203
	v_mfma_f32_16x16x32_fp8_fp8 v[148:151], v[150:151], v[196:197], v[136:139]
	ds_read2_b32 v[202:203], v190 offset0:144 offset1:146
	ds_read_b128 v[194:197], v164 offset:1344
	s_nop 0
	v_lshlrev_b64 v[136:137], 11, v[146:147]
	s_waitcnt vmcnt(29) lgkmcnt(2)
	v_mfma_f32_16x16x32_fp8_fp8 v[140:143], v[132:133], v[198:199], v[140:143]
	v_lshl_add_u64 v[132:133], v[168:169], 0, v[136:137]
	global_load_dwordx4 v[136:139], v[144:145], off
	s_nop 0
	global_load_dwordx4 v[144:147], v[132:133], off
	s_waitcnt vmcnt(29)
	v_mfma_f32_16x16x32_fp8_fp8 v[148:151], v[124:125], v[198:199], v[148:151]
	s_waitcnt lgkmcnt(1)
	v_ashrrev_i32_e32 v199, 31, v203
	v_mov_b32_e32 v198, v203
	v_ashrrev_i32_e32 v125, 31, v202
	v_mfma_f32_16x16x32_fp8_fp8 v[132:135], v[134:135], v[200:201], v[140:143]
	v_mov_b32_e32 v124, v202
	v_lshlrev_b64 v[124:125], 11, v[124:125]
	v_lshl_add_u64 v[124:125], v[168:169], 0, v[124:125]
	v_mfma_f32_16x16x32_fp8_fp8 v[140:143], v[126:127], v[200:201], v[148:151]
	v_lshlrev_b64 v[126:127], 11, v[198:199]
	ds_read2_b32 v[198:199], v190 offset0:148 offset1:150
	v_lshl_add_u64 v[126:127], v[168:169], 0, v[126:127]
	s_waitcnt lgkmcnt(1)
	v_mfma_f32_16x16x32_fp8_fp8 v[148:151], v[116:117], v[194:195], v[132:135]
	s_nop 2
	global_load_dwordx4 v[132:135], v[124:125], off
	s_nop 0
	global_load_dwordx4 v[124:127], v[126:127], off
	s_waitcnt lgkmcnt(0)
	v_ashrrev_i32_e32 v117, 31, v198
	s_waitcnt vmcnt(30)
	v_mfma_f32_16x16x32_fp8_fp8 v[140:143], v[104:105], v[194:195], v[140:143]
	v_mov_b32_e32 v116, v198
	v_lshlrev_b64 v[104:105], 11, v[116:117]
	v_lshl_add_u64 v[202:203], v[168:169], 0, v[104:105]
	v_mfma_f32_16x16x32_fp8_fp8 v[116:119], v[118:119], v[196:197], v[148:151]
	v_ashrrev_i32_e32 v195, 31, v199
	v_mov_b32_e32 v194, v199
	s_nop 0
	ds_read_b128 v[148:151], v164 offset:1408
	v_mfma_f32_16x16x32_fp8_fp8 v[104:107], v[106:107], v[196:197], v[140:143]
	s_waitcnt vmcnt(29) lgkmcnt(0)
	v_mfma_f32_16x16x32_fp8_fp8 v[198:201], v[92:93], v[148:149], v[116:119]
	s_nop 0
	v_lshlrev_b64 v[140:141], 11, v[194:195]
	ds_read2_b32 v[204:205], v190 offset0:152 offset1:154
	ds_read_b128 v[194:197], v164 offset:1472
	v_lshl_add_u64 v[92:93], v[168:169], 0, v[140:141]
	s_waitcnt vmcnt(27)
	v_mfma_f32_16x16x32_fp8_fp8 v[104:107], v[84:85], v[148:149], v[104:107]
	global_load_dwordx4 v[140:143], v[202:203], off
	global_load_dwordx4 v[116:119], v[92:93], off
	s_waitcnt lgkmcnt(1)
	v_ashrrev_i32_e32 v85, 31, v204
	v_mov_b32_e32 v84, v204
	v_mfma_f32_16x16x32_fp8_fp8 v[92:95], v[94:95], v[150:151], v[198:201]
	v_lshlrev_b64 v[84:85], 11, v[84:85]
	v_lshl_add_u64 v[84:85], v[168:169], 0, v[84:85]
	s_nop 0
	v_ashrrev_i32_e32 v199, 31, v205
	v_mov_b32_e32 v198, v205
	v_mfma_f32_16x16x32_fp8_fp8 v[148:151], v[86:87], v[150:151], v[104:107]
	v_lshlrev_b64 v[86:87], 11, v[198:199]
	ds_read2_b32 v[198:199], v190 offset0:156 offset1:158
	v_lshl_add_u64 v[86:87], v[168:169], 0, v[86:87]
	s_waitcnt lgkmcnt(1)
	v_mfma_f32_16x16x32_fp8_fp8 v[92:95], v[80:81], v[194:195], v[92:95]
	global_load_dwordx4 v[104:107], v[84:85], off
	s_nop 0
	global_load_dwordx4 v[84:87], v[86:87], off
	s_waitcnt lgkmcnt(0)
	v_ashrrev_i32_e32 v81, 31, v198
	s_waitcnt vmcnt(30)
	v_mfma_f32_16x16x32_fp8_fp8 v[148:151], v[76:77], v[194:195], v[148:151]
	v_mov_b32_e32 v80, v198
	v_lshlrev_b64 v[76:77], 11, v[80:81]
	v_lshl_add_u64 v[202:203], v[168:169], 0, v[76:77]
	v_mfma_f32_16x16x32_fp8_fp8 v[80:83], v[82:83], v[196:197], v[92:95]
	s_nop 2
	v_ashrrev_i32_e32 v93, 31, v199
	v_mov_b32_e32 v92, v199
	ds_read_b128 v[198:201], v164 offset:1536
	v_mfma_f32_16x16x32_fp8_fp8 v[76:79], v[78:79], v[196:197], v[148:151]
	ds_read2_b32 v[204:205], v190 offset0:160 offset1:162
	s_nop 1
	ds_read_b128 v[148:151], v164 offset:1600
	v_lshlrev_b64 v[92:93], 11, v[92:93]
	s_waitcnt vmcnt(29) lgkmcnt(2)
	v_mfma_f32_16x16x32_fp8_fp8 v[194:197], v[72:73], v[198:199], v[80:83]
	v_lshl_add_u64 v[72:73], v[168:169], 0, v[92:93]
	global_load_dwordx4 v[92:95], v[202:203], off
	s_nop 0
	global_load_dwordx4 v[80:83], v[72:73], off
	s_waitcnt vmcnt(29)
	v_mfma_f32_16x16x32_fp8_fp8 v[76:79], v[68:69], v[198:199], v[76:79]
	s_waitcnt lgkmcnt(1)
; __device__ __forceinline__ long mk64(unsigned lo, unsigned hi) { return (long)(((u64)hi << 32) | (u64)lo); }
; #define MFMA8(a, b, c) __builtin_amdgcn_mfma_f32_16x16x32_fp8_fp8(a, b, c, 0, 0, 0)
; __device__ __forceinline__ void phase_peerout(const Params& p, char* smem, float* dstbase) {
;     ...
;       for (int kq = 0; kq < 16; ++kq) {
;         const u32x4 c0 = ring[kq & 7][0], c1 = ring[kq & 7][1], c2 = ring[kq & 7][2], c3 = ring[kq & 7][3];
;         if (kq + 8 < 16) {
;           ring[kq & 7][0] = *(const u32x4*)(rp0 + (kq + 8) * 128);
;           ring[kq & 7][1] = *(const u32x4*)(rp0 + (kq + 8) * 128 + 64);
;           ring[kq & 7][2] = *(const u32x4*)(rp1 + (kq + 8) * 128);
;           ring[kq & 7][3] = *(const u32x4*)(rp1 + (kq + 8) * 128 + 64);
;         } else {
; #pragma unroll
;           for (int j = 0; j < 4; ++j) {
;             const int i = (kq - 8) * 4 + j;
;             vpre[i] = *(const u32x4*)(v8 + (size_t)eix[2 * i + (tid >> 7)] * D + (tid & 127) * 16);
;           }
;         }
;         const u32x4 x0 = *(const u32x4*)(xsel + kq * 128 + fq * 16), x1v = *(const u32x4*)(xsel + kq * 128 + fq * 16 + 64);
;         long b;
;         b = mk64(x0[0], x0[1]);
;         ah0 = MFMA8(mk64(c0[0], c0[1]), b, ah0); ah1 = MFMA8(mk64(c2[0], c2[1]), b, ah1);
;         b = mk64(x0[2], x0[3]);
;         ah0 = MFMA8(mk64(c0[2], c0[3]), b, ah0); ah1 = MFMA8(mk64(c2[2], c2[3]), b, ah1);
;         b = mk64(x1v[0], x1v[1]);
;         ah0 = MFMA8(mk64(c1[0], c1[1]), b, ah0); ah1 = MFMA8(mk64(c3[0], c3[1]), b, ah1);
;         b = mk64(x1v[2], x1v[3]);
;         ah0 = MFMA8(mk64(c1[2], c1[3]), b, ah0); ah1 = MFMA8(mk64(c3[2], c3[3]), b, ah1);
;       }
;       {
;         const int jsel = fr & 3;
;         const float s0 = jsel == 0 ? ah0[0] : jsel == 1 ? ah0[1] : jsel == 2 ? ah0[2] : ah0[3];
;         const float s1 = jsel == 0 ? ah1[0] : jsel == 1 ? ah1[1] : jsel == 2 ? ah1[2] : ah1[3];
	v_ashrrev_i32_e32 v199, 31, v205
	v_mov_b32_e32 v198, v205
	v_ashrrev_i32_e32 v69, 31, v204
	v_mfma_f32_16x16x32_fp8_fp8 v[72:75], v[74:75], v[200:201], v[194:197]
	v_mov_b32_e32 v68, v204
	v_lshlrev_b64 v[68:69], 11, v[68:69]
	v_lshl_add_u64 v[68:69], v[168:169], 0, v[68:69]
	v_mfma_f32_16x16x32_fp8_fp8 v[194:197], v[70:71], v[200:201], v[76:79]
	v_lshlrev_b64 v[70:71], 11, v[198:199]
	ds_read2_b32 v[198:199], v190 offset0:164 offset1:166
	v_lshl_add_u64 v[70:71], v[168:169], 0, v[70:71]
	s_waitcnt lgkmcnt(1)
	v_mfma_f32_16x16x32_fp8_fp8 v[72:75], v[64:65], v[148:149], v[72:75]
	global_load_dwordx4 v[76:79], v[68:69], off
	s_nop 0
	global_load_dwordx4 v[68:71], v[70:71], off
	s_waitcnt lgkmcnt(0)
	v_ashrrev_i32_e32 v65, 31, v198
	s_waitcnt vmcnt(30)
	v_mfma_f32_16x16x32_fp8_fp8 v[194:197], v[60:61], v[148:149], v[194:197]
	v_mov_b32_e32 v64, v198
	v_lshlrev_b64 v[60:61], 11, v[64:65]
	v_lshl_add_u64 v[202:203], v[168:169], 0, v[60:61]
	v_mfma_f32_16x16x32_fp8_fp8 v[64:67], v[66:67], v[150:151], v[72:75]
	s_nop 2
	v_ashrrev_i32_e32 v73, 31, v199
	v_mov_b32_e32 v72, v199
	ds_read_b128 v[198:201], v164 offset:1664
	v_mfma_f32_16x16x32_fp8_fp8 v[60:63], v[62:63], v[150:151], v[194:197]
	ds_read2_b32 v[204:205], v190 offset0:168 offset1:170
	ds_read_b128 v[148:151], v164 offset:1728
	v_lshlrev_b64 v[72:73], 11, v[72:73]
	s_waitcnt vmcnt(29) lgkmcnt(2)
	v_mfma_f32_16x16x32_fp8_fp8 v[194:197], v[56:57], v[198:199], v[64:67]
	v_lshl_add_u64 v[56:57], v[168:169], 0, v[72:73]
	global_load_dwordx4 v[72:75], v[202:203], off
	s_nop 0
	global_load_dwordx4 v[64:67], v[56:57], off
	s_waitcnt vmcnt(29)
	v_mfma_f32_16x16x32_fp8_fp8 v[60:63], v[52:53], v[198:199], v[60:63]
	s_waitcnt lgkmcnt(1)
	v_ashrrev_i32_e32 v199, 31, v205
	v_mov_b32_e32 v198, v205
	v_ashrrev_i32_e32 v53, 31, v204
	v_mfma_f32_16x16x32_fp8_fp8 v[56:59], v[58:59], v[200:201], v[194:197]
	v_mov_b32_e32 v52, v204
	v_lshlrev_b64 v[52:53], 11, v[52:53]
	v_lshl_add_u64 v[52:53], v[168:169], 0, v[52:53]
	v_mfma_f32_16x16x32_fp8_fp8 v[194:197], v[54:55], v[200:201], v[60:63]
	v_lshlrev_b64 v[54:55], 11, v[198:199]
	ds_read2_b32 v[198:199], v190 offset0:172 offset1:174
	v_lshl_add_u64 v[54:55], v[168:169], 0, v[54:55]
	s_waitcnt lgkmcnt(1)
	v_mfma_f32_16x16x32_fp8_fp8 v[56:59], v[48:49], v[148:149], v[56:59]
	global_load_dwordx4 v[60:63], v[52:53], off
	s_nop 0
	global_load_dwordx4 v[52:55], v[54:55], off
	s_waitcnt lgkmcnt(0)
	v_ashrrev_i32_e32 v49, 31, v198
	v_mov_b32_e32 v48, v198
	s_waitcnt vmcnt(30)
	v_mfma_f32_16x16x32_fp8_fp8 v[194:197], v[40:41], v[148:149], v[194:197]
	v_lshlrev_b64 v[40:41], 11, v[48:49]
	v_lshl_add_u64 v[202:203], v[168:169], 0, v[40:41]
	v_ashrrev_i32_e32 v41, 31, v199
	v_mov_b32_e32 v40, v199
	ds_read_b128 v[198:201], v164 offset:1792
	v_mfma_f32_16x16x32_fp8_fp8 v[48:51], v[50:51], v[150:151], v[56:59]
	s_nop 2
	v_lshlrev_b64 v[56:57], 11, v[40:41]
	v_mfma_f32_16x16x32_fp8_fp8 v[40:43], v[42:43], v[150:151], v[194:197]
	ds_read2_b32 v[206:207], v190 offset0:176 offset1:178
	ds_read_b128 v[148:151], v164 offset:1856
	v_lshl_add_u64 v[204:205], v[168:169], 0, v[56:57]
	s_waitcnt vmcnt(29) lgkmcnt(2)
	v_mfma_f32_16x16x32_fp8_fp8 v[194:197], v[36:37], v[198:199], v[48:51]
	global_load_dwordx4 v[56:59], v[202:203], off
	s_nop 1
	global_load_dwordx4 v[48:51], v[204:205], off
	s_waitcnt lgkmcnt(1)
	v_ashrrev_i32_e32 v37, 31, v206
	v_mov_b32_e32 v36, v206
	s_waitcnt vmcnt(29)
	v_mfma_f32_16x16x32_fp8_fp8 v[40:43], v[44:45], v[198:199], v[40:43]
	ds_read2_b32 v[198:199], v190 offset0:180 offset1:182
	v_ashrrev_i32_e32 v45, 31, v207
	v_mov_b32_e32 v44, v207
	v_mfma_f32_16x16x32_fp8_fp8 v[194:197], v[38:39], v[200:201], v[194:197]
	v_lshlrev_b64 v[36:37], 11, v[36:37]
	v_lshlrev_b64 v[38:39], 11, v[44:45]
	v_lshl_add_u64 v[36:37], v[168:169], 0, v[36:37]
	v_mfma_f32_16x16x32_fp8_fp8 v[40:43], v[46:47], v[200:201], v[40:43]
	v_lshl_add_u64 v[38:39], v[168:169], 0, v[38:39]
	global_load_dwordx4 v[44:47], v[36:37], off
	s_nop 0
	global_load_dwordx4 v[36:39], v[38:39], off
	ds_read2_b32 v[202:203], v190 offset0:184 offset1:186
	s_waitcnt lgkmcnt(2)
	v_mfma_f32_16x16x32_fp8_fp8 v[194:197], v[28:29], v[148:149], v[194:197]
	s_waitcnt lgkmcnt(1)
	v_ashrrev_i32_e32 v29, 31, v198
	v_mov_b32_e32 v28, v198
	v_lshlrev_b64 v[28:29], 11, v[28:29]
	s_waitcnt vmcnt(30)
	v_mfma_f32_16x16x32_fp8_fp8 v[40:43], v[32:33], v[148:149], v[40:43]
	v_lshl_add_u64 v[32:33], v[168:169], 0, v[28:29]
	v_ashrrev_i32_e32 v149, 31, v199
	v_mov_b32_e32 v148, v199
	v_mfma_f32_16x16x32_fp8_fp8 v[28:31], v[30:31], v[150:151], v[194:197]
	v_lshlrev_b64 v[148:149], 11, v[148:149]
	v_lshl_add_u64 v[198:199], v[168:169], 0, v[148:149]
	s_nop 0
	ds_read_b128 v[194:197], v164 offset:1920
	v_mfma_f32_16x16x32_fp8_fp8 v[148:151], v[34:35], v[150:151], v[40:43]
	s_nop 2
	global_load_dwordx4 v[40:43], v[32:33], off
	s_nop 0
	global_load_dwordx4 v[32:35], v[198:199], off
	ds_read_b128 v[198:201], v164 offset:1984
	ds_read2_b32 v[206:207], v190 offset0:188 offset1:190
	s_waitcnt vmcnt(31) lgkmcnt(2)
	v_mfma_f32_16x16x32_fp8_fp8 v[28:31], v[24:25], v[194:195], v[28:31]
	v_ashrrev_i32_e32 v25, 31, v202
	v_mov_b32_e32 v24, v202
	v_lshlrev_b64 v[24:25], 11, v[24:25]
	s_waitcnt vmcnt(29)
	v_mfma_f32_16x16x32_fp8_fp8 v[148:151], v[20:21], v[194:195], v[148:151]
	v_ashrrev_i32_e32 v21, 31, v203
	v_mov_b32_e32 v20, v203
	v_lshlrev_b64 v[20:21], 11, v[20:21]
	v_mfma_f32_16x16x32_fp8_fp8 v[202:205], v[26:27], v[196:197], v[28:31]
	v_lshl_add_u64 v[26:27], v[168:169], 0, v[20:21]
	s_waitcnt lgkmcnt(0)
	v_ashrrev_i32_e32 v195, 31, v206
	v_mov_b32_e32 v194, v206
	v_mfma_f32_16x16x32_fp8_fp8 v[20:23], v[22:23], v[196:197], v[148:151]
	v_lshl_add_u64 v[24:25], v[168:169], 0, v[24:25]
	global_load_dwordx4 v[28:31], v[24:25], off
	s_nop 0
	global_load_dwordx4 v[24:27], v[26:27], off
	v_mfma_f32_16x16x32_fp8_fp8 v[148:151], v[16:17], v[198:199], v[202:205]
	v_lshlrev_b64 v[16:17], 11, v[194:195]
	v_lshl_add_u64 v[16:17], v[168:169], 0, v[16:17]
	s_nop 0
	v_ashrrev_i32_e32 v203, 31, v207
	v_mov_b32_e32 v202, v207
	s_waitcnt vmcnt(30)
	v_mfma_f32_16x16x32_fp8_fp8 v[194:197], v[100:101], v[198:199], v[20:23]
	s_nop 2
	v_lshlrev_b64 v[20:21], 11, v[202:203]
	v_lshl_add_u64 v[100:101], v[168:169], 0, v[20:21]
	v_mfma_f32_16x16x32_fp8_fp8 v[148:151], v[18:19], v[200:201], v[148:151]
	global_load_dwordx4 v[20:23], v[16:17], off
	s_nop 0
	global_load_dwordx4 v[16:19], v[100:101], off
	v_mfma_f32_16x16x32_fp8_fp8 v[100:103], v[102:103], v[200:201], v[194:197]
	s_setprio 0
	s_and_saveexec_b64 s[38:39], s[4:5]
	s_xor_b64 s[38:39], exec, s[38:39]
	s_cbranch_execz .LBB0_1257
	s_nop 0
	v_mov_b32_e32 v148, v149
	s_and_saveexec_b64 s[40:41], s[6:7]
	s_xor_b64 s[40:41], exec, s[40:41]
	v_cndmask_b32_e64 v148, v151, v150, s[8:9]
	s_andn2_saveexec_b64 s[40:41], s[40:41]
	s_or_b64 exec, exec, s[40:41]
